# q-proj epilogue: preload all 8 row ssq values at once; Q loads as global_load
# baseline (speedup 1.0000x reference)
.LBB0_132:
	s_and_b32 s5, s64, 7
	s_lshl_b32 s0, s5, 8
	s_or_b32 s22, s14, s0
	s_mov_b32 s23, s15
	s_lshl_b64 s[0:1], s[22:23], 10
	s_add_u32 s0, s55, s0
	s_addc_u32 s1, s56, s1
	s_lshl_b32 s4, s64, 4
	s_and_b32 s65, s4, 0x180
	s_lshl_b32 s4, s65, 1
	s_add_u32 s30, s0, s4
	s_addc_u32 s31, s1, 0
	s_lshl_b64 s[0:1], s[2:3], 21
	s_add_u32 s3, s57, s0
	s_addc_u32 s6, s58, s1
	s_add_u32 s24, s3, s4
	s_addc_u32 s25, s6, 0
	v_mov_b32_e32 v121, v218
	s_add_u32 s0, s90, s0
	v_mov_b32_e32 v4, v218
	s_addc_u32 s1, s91, s1
	s_add_u32 s3, s0, s4
	v_ashrrev_i32_e32 v0, 6, v4
	v_and_b32_e32 v6, 31, v4
	v_readfirstlane_b32 s0, v0
	v_lshl_or_b32 v0, v0, 5, v6
	v_ashrrev_i32_e32 v1, 31, v0
	v_lshlrev_b64 v[0:1], 10, v[0:1]
	v_lshrrev_b32_e32 v7, 1, v4
	v_and_b32_e32 v5, 63, v4
	v_lshl_add_u64 v[0:1], s[30:31], 0, v[0:1]
	v_and_b32_e32 v184, 16, v7
	s_addc_u32 s66, s1, 0
	v_lshl_add_u64 v[0:1], v[0:1], 0, v[184:185]
	s_lshl_b32 s1, s0, 10
	v_lshlrev_b32_e32 v8, 4, v5
	global_load_dwordx4 v[96:99], v[0:1], off
	global_load_dwordx4 v[100:103], v[0:1], off offset:32
	global_load_dwordx4 v[104:107], v[0:1], off offset:64
	global_load_dwordx4 v[108:111], v[0:1], off offset:96
	v_or_b32_e32 v0, s1, v8
	v_ashrrev_i32_e32 v1, 31, v0
	v_lshrrev_b32_e32 v1, 25, v1
	v_add_u32_e32 v1, v0, v1
	v_lshlrev_b32_e32 v9, 3, v5
	s_lshl_b32 s0, s0, 6
	v_ashrrev_i32_e32 v2, 7, v1
	v_and_b32_e32 v1, 0xffffff80, v1
	v_and_b32_e32 v3, 32, v4
	s_and_b32 s0, s0, 64
	v_and_b32_e32 v10, 24, v9
	v_sub_u32_e32 v0, v0, v1
	v_or3_b32 v3, v10, v3, s0
	s_ashr_i32 s0, s1, 8
	v_ashrrev_i32_e32 v0, 4, v0
	v_lshrrev_b32_e32 v1, 1, v2
	s_and_b32 s6, s0, 0x7ffff0
	s_lshr_b32 s0, s0, 1
	v_bitop3_b32 v0, v1, v0, 7 bitop3:0x6c
	v_bfe_u32 v1, v4, 2, 2
	s_and_b32 s0, s0, 4
	v_and_or_b32 v1, v7, 8, v1
	s_or_b32 s0, s6, s0
	v_or_b32_e32 v10, s0, v1
	s_add_i32 s0, s1, 0x2000
	s_ashr_i32 s0, s0, 8
	s_and_b32 s6, s0, 0x7ffff0
	s_lshr_b32 s0, s0, 1
	s_and_b32 s0, s0, 4
	s_or_b32 s0, s6, s0
	s_add_i32 s4, 0, 0x14000
	v_or_b32_e32 v1, s0, v1
	s_lshl_b32 s0, s5, 17
	s_lshl_b32 s6, s5, 18
	v_lshl_or_b32 v114, v1, 9, v3
	v_lshlrev_b32_e32 v1, 9, v2
	s_add_u32 s68, s24, s6
	v_lshl_add_u32 v0, v0, 3, v1
	s_addc_u32 s69, s25, 0
	s_add_i32 s5, s1, 0
	v_ashrrev_i32_e32 v1, 31, v0
	s_add_i32 m0, s5, 0x8000
	v_lshl_or_b32 v112, v10, 9, v3
	v_lshlrev_b64 v[0:1], 1, v[0:1]
	s_add_u32 s34, s3, s6
	v_lshl_add_u64 v[2:3], s[68:69], 0, v[0:1]
	s_addc_u32 s35, s66, 0
	v_ashrrev_i32_e32 v113, 31, v112
	s_waitcnt lgkmcnt(0)
	s_barrier
	global_load_lds_dwordx4 v[2:3], off
	v_lshl_add_u64 v[2:3], v[112:113], 1, s[34:35]
	s_mov_b32 m0, s5
	v_ashrrev_i32_e32 v115, 31, v114
	global_load_lds_dwordx4 v[2:3], off
	v_lshl_add_u64 v[2:3], v[114:115], 1, s[34:35]
	s_add_i32 m0, s5, 0x2000
	s_cmp_lg_u32 0, -1
	global_load_lds_dwordx4 v[2:3], off
	v_and_b32_e32 v2, 0x3fffffc0, v4
	v_lshl_add_u32 v119, v2, 2, s4
	v_lshlrev_b32_e32 v2, 1, v4
	s_cselect_b32 s1, 0, 0
	v_and_b32_e32 v2, 32, v2
	v_lshlrev_b32_e32 v4, 3, v4
	s_add_i32 s6, s1, 0x8000
	s_movk_i32 s54, 0x118
	v_and_b32_e32 v3, 0xc0, v8
	s_waitcnt vmcnt(0)
	v_and_b32_e32 v4, 0x70, v4
	v_lshl_add_u32 v120, v6, 7, s6
	s_movk_i32 s6, 0x60
	v_lshl_add_u64 v[116:117], s[24:25], 0, v[0:1]
	v_and_or_b32 v0, v9, s54, v2
	v_mov_b32_e32 v14, v185
	v_mov_b32_e32 v15, v185
	v_bitop3_b32 v123, v7, v4, 16 bitop3:0x6c
	v_bitop3_b32 v124, v184, v4, 32 bitop3:0x36
	v_bitop3_b32 v125, v184, v4, 64 bitop3:0x36
	v_bitop3_b32 v126, v184, v4, s6 bitop3:0x36
	v_cmp_gt_u32_e64 s[6:7], 32, v5
	v_lshl_add_u32 v122, v6, 2, v119
	v_add3_u32 v127, v3, s1, v0
	s_or_b32 s67, s0, 0x8000
	v_mov_b32_e32 v0, v185
	v_mov_b32_e32 v1, v185
	v_mov_b32_e32 v2, v185
	v_mov_b32_e32 v3, v185
	v_mov_b32_e32 v4, v185
	v_mov_b32_e32 v5, v185
	v_mov_b32_e32 v6, v185
	v_mov_b32_e32 v7, v185
	v_mov_b32_e32 v8, v185
	v_mov_b32_e32 v9, v185
	v_mov_b32_e32 v10, v185
	v_mov_b32_e32 v11, v185
	v_mov_b32_e32 v12, v185
	v_mov_b32_e32 v13, v185
	v_mov_b64_e32 v[30:31], v[14:15]
	v_mov_b64_e32 v[46:47], v[14:15]
	v_mov_b64_e32 v[62:63], v[14:15]
	s_mov_b32 s53, 0
	v_mov_b32_e32 v128, 0
	v_mov_b32_e32 v160, 0x80000000
	v_mov_b32_e32 v161, 0x80000000
	v_mov_b32_e32 v162, 0x80000000
	v_mov_b32_e32 v163, 0x80000000
	v_mov_b32_e32 v164, 0x80000000
	v_mov_b32_e32 v165, 0x80000000
	v_mov_b32_e32 v166, 0x80000000
	v_mov_b32_e32 v167, 0x80000000
	v_mov_b32_e32 v168, 0x80000000
	v_mov_b32_e32 v169, 0x80000000
	v_mov_b32_e32 v170, 0x80000000
	v_mov_b32_e32 v171, 0x80000000
	v_mov_b32_e32 v172, 0x80000000
	v_mov_b32_e32 v173, 0x80000000
	v_mov_b32_e32 v174, 0x80000000
	v_mov_b32_e32 v175, 0x80000000
	s_mov_b32 s54, s67
	v_mov_b64_e32 v[28:29], v[12:13]
	v_mov_b64_e32 v[26:27], v[10:11]
	v_mov_b64_e32 v[24:25], v[8:9]
	v_mov_b64_e32 v[22:23], v[6:7]
	v_mov_b64_e32 v[20:21], v[4:5]
	v_mov_b64_e32 v[18:19], v[2:3]
	v_mov_b64_e32 v[16:17], v[0:1]
	v_mov_b64_e32 v[44:45], v[12:13]
	v_mov_b64_e32 v[42:43], v[10:11]
	v_mov_b64_e32 v[40:41], v[8:9]
	v_mov_b64_e32 v[38:39], v[6:7]
	v_mov_b64_e32 v[36:37], v[4:5]
	v_mov_b64_e32 v[34:35], v[2:3]
	v_mov_b64_e32 v[32:33], v[0:1]
	v_mov_b64_e32 v[60:61], v[12:13]
	v_mov_b64_e32 v[58:59], v[10:11]
	v_mov_b64_e32 v[56:57], v[8:9]
	v_mov_b64_e32 v[54:55], v[6:7]
	v_mov_b64_e32 v[52:53], v[4:5]
	v_mov_b64_e32 v[50:51], v[2:3]
	v_mov_b64_e32 v[48:49], v[0:1]
	v_mov_b32_e32 v129, 0
	s_waitcnt vmcnt(0) lgkmcnt(0)
	s_barrier
	s_and_b32 s80, s53, 1
	s_cmp_eq_u32 s53, 31
	s_movk_i32 s0, 0x2000
	s_cbranch_scc1 .LBB0_134

.LBB0_148:
	s_and_saveexec_b64 s[0:1], s[6:7]
	ds_write_b32 v122, v64
	s_or_b64 exec, exec, s[0:1]
	v_lshlrev_b32_e32 v64, 6, v121
	v_ashrrev_i32_e32 v65, 31, v64
	s_waitcnt lgkmcnt(0)
	v_add_u32_e32 v80, v119, v184
	v_lshl_add_u64 v[112:113], v[64:65], 2, s[12:13]
	ds_read_b128 v[64:67], v80
	ds_read_b128 v[68:71], v80 offset:32
	s_mov_b32 s5, 0
	v_mov_b32_e32 v130, 0
	v_mov_b32_e32 v131, 0
	s_waitcnt lgkmcnt(1)
	v_rcp_f32_e32 v72, v64
	v_rcp_f32_e32 v73, v65
	v_rcp_f32_e32 v74, v66
	v_rcp_f32_e32 v75, v67
	ds_read_b128 v[64:67], v80 offset:64
	s_waitcnt lgkmcnt(1)
	v_rcp_f32_e32 v68, v68
	v_rcp_f32_e32 v69, v69
	v_rcp_f32_e32 v70, v70
	v_rcp_f32_e32 v71, v71
	s_waitcnt lgkmcnt(0)
	v_rcp_f32_e32 v76, v64
	v_rcp_f32_e32 v77, v65
	v_rcp_f32_e32 v78, v66
	v_rcp_f32_e32 v79, v67
	ds_read_b128 v[64:67], v80 offset:96
	v_pk_mul_f32 v[48:49], v[48:49], v[72:73]
	v_pk_mul_f32 v[50:51], v[50:51], v[74:75]
	v_pk_mul_f32 v[32:33], v[32:33], v[72:73]
	v_pk_mul_f32 v[34:35], v[34:35], v[74:75]
	s_waitcnt lgkmcnt(0)
	v_rcp_f32_e32 v64, v64
	v_rcp_f32_e32 v65, v65
	v_rcp_f32_e32 v66, v66
	v_rcp_f32_e32 v67, v67
	v_pk_mul_f32 v[16:17], v[16:17], v[72:73]
	v_pk_mul_f32 v[18:19], v[18:19], v[74:75]
	v_pk_mul_f32 v[0:1], v[0:1], v[72:73]
	v_pk_mul_f32 v[2:3], v[2:3], v[74:75]
	flat_store_dwordx4 v[112:113], v[48:51]
	flat_store_dwordx4 v[112:113], v[32:35] offset:64
	flat_store_dwordx4 v[112:113], v[16:19] offset:128
	v_pk_mul_f32 v[48:49], v[52:53], v[68:69]
	v_pk_mul_f32 v[50:51], v[54:55], v[70:71]
	v_pk_mul_f32 v[32:33], v[36:37], v[68:69]
	v_pk_mul_f32 v[34:35], v[38:39], v[70:71]
	v_pk_mul_f32 v[16:17], v[20:21], v[68:69]
	v_pk_mul_f32 v[18:19], v[22:23], v[70:71]
	flat_store_dwordx4 v[112:113], v[0:3] offset:192
	flat_store_dwordx4 v[112:113], v[48:51] offset:16
	flat_store_dwordx4 v[112:113], v[32:35] offset:80
	v_pk_mul_f32 v[0:1], v[4:5], v[68:69]
	v_pk_mul_f32 v[2:3], v[6:7], v[70:71]
	v_pk_mul_f32 v[48:49], v[56:57], v[76:77]
	v_pk_mul_f32 v[50:51], v[58:59], v[78:79]
	v_pk_mul_f32 v[32:33], v[40:41], v[76:77]
	v_pk_mul_f32 v[34:35], v[42:43], v[78:79]
	flat_store_dwordx4 v[112:113], v[16:19] offset:144
	flat_store_dwordx4 v[112:113], v[0:3] offset:208
	flat_store_dwordx4 v[112:113], v[48:51] offset:32
	v_pk_mul_f32 v[16:17], v[24:25], v[76:77]
	v_pk_mul_f32 v[18:19], v[26:27], v[78:79]
	v_pk_mul_f32 v[0:1], v[8:9], v[76:77]
	v_pk_mul_f32 v[2:3], v[10:11], v[78:79]
	v_pk_mul_f32 v[48:49], v[60:61], v[64:65]
	v_pk_mul_f32 v[50:51], v[62:63], v[66:67]
	flat_store_dwordx4 v[112:113], v[32:35] offset:96
	flat_store_dwordx4 v[112:113], v[16:19] offset:160
	flat_store_dwordx4 v[112:113], v[0:3] offset:224
	v_pk_mul_f32 v[32:33], v[44:45], v[64:65]
	v_pk_mul_f32 v[34:35], v[46:47], v[66:67]
	v_pk_mul_f32 v[16:17], v[28:29], v[64:65]
	v_pk_mul_f32 v[18:19], v[30:31], v[66:67]
	v_pk_mul_f32 v[0:1], v[12:13], v[64:65]
	v_pk_mul_f32 v[2:3], v[14:15], v[66:67]
	v_mov_b32_e32 v4, v218
	flat_store_dwordx4 v[112:113], v[48:51] offset:48
	flat_store_dwordx4 v[112:113], v[32:35] offset:112
	flat_store_dwordx4 v[112:113], v[16:19] offset:176
	flat_store_dwordx4 v[112:113], v[0:3] offset:240
	v_mov_b32_e32 v14, v185
	v_and_b32_e32 v6, 31, v4
	v_and_b32_e32 v0, 0x3fffffc0, v4
	v_lshl_add_u32 v122, v0, 2, s4
	v_ashrrev_i32_e32 v0, 6, v4
	v_lshrrev_b32_e32 v7, 1, v4
	v_readfirstlane_b32 s0, v0
	v_lshl_or_b32 v0, v0, 5, v6
	v_ashrrev_i32_e32 v1, 31, v0
	v_lshlrev_b64 v[0:1], 10, v[0:1]
	v_and_b32_e32 v5, 63, v4
	v_lshl_add_u64 v[0:1], s[30:31], 0, v[0:1]
	v_and_b32_e32 v184, 16, v7
	v_lshl_add_u64 v[0:1], v[0:1], 0, v[184:185]
	s_lshl_b32 s1, s0, 10
	v_lshlrev_b32_e32 v8, 4, v5
	global_load_dwordx4 v[96:99], v[0:1], off offset:128
	global_load_dwordx4 v[100:103], v[0:1], off offset:160
	global_load_dwordx4 v[104:107], v[0:1], off offset:192
	global_load_dwordx4 v[108:111], v[0:1], off offset:224
	v_or_b32_e32 v0, s1, v8
	v_ashrrev_i32_e32 v1, 31, v0
	v_lshrrev_b32_e32 v1, 25, v1
	v_add_u32_e32 v1, v0, v1
	v_lshlrev_b32_e32 v9, 3, v5
	s_lshl_b32 s0, s0, 6
	v_ashrrev_i32_e32 v2, 7, v1
	v_and_b32_e32 v1, 0xffffff80, v1
	v_and_b32_e32 v3, 32, v4
	s_and_b32 s0, s0, 64
	v_and_b32_e32 v10, 24, v9
	v_sub_u32_e32 v0, v0, v1
	v_or3_b32 v3, v10, v3, s0
	s_ashr_i32 s0, s1, 8
	v_ashrrev_i32_e32 v0, 4, v0
	v_lshrrev_b32_e32 v1, 1, v2
	s_and_b32 s4, s0, 0x7ffff0
	s_lshr_b32 s0, s0, 1
	v_bitop3_b32 v0, v1, v0, 7 bitop3:0x6c
	v_bfe_u32 v1, v4, 2, 2
	s_and_b32 s0, s0, 4
	v_and_or_b32 v1, v7, 8, v1
	s_or_b32 s0, s4, s0
	v_or_b32_e32 v10, s0, v1
	s_add_i32 s0, s1, 0x2000
	s_ashr_i32 s0, s0, 8
	s_and_b32 s4, s0, 0x7ffff0
	s_lshr_b32 s0, s0, 1
	s_and_b32 s0, s0, 4
	s_or_b32 s0, s4, s0
	v_or_b32_e32 v1, s0, v1
	v_lshl_or_b32 v116, v1, 9, v3
	v_lshlrev_b32_e32 v1, 9, v2
	v_lshl_add_u32 v0, v0, 3, v1
	v_ashrrev_i32_e32 v1, 31, v0
	v_lshlrev_b64 v[0:1], 1, v[0:1]
	v_lshl_or_b32 v114, v10, 9, v3
	v_lshl_add_u64 v[2:3], s[68:69], 0, v[0:1]
	s_add_i32 s4, s1, 0
	v_lshl_add_u64 v[2:3], v[2:3], 0, s[78:79]
	s_add_i32 m0, s4, 0x8000
	v_ashrrev_i32_e32 v115, 31, v114
	s_waitcnt lgkmcnt(0)
	s_barrier
	global_load_lds_dwordx4 v[2:3], off
	v_lshl_add_u64 v[2:3], v[114:115], 1, s[34:35]
	s_mov_b32 m0, s4
	v_ashrrev_i32_e32 v117, 31, v116
	global_load_lds_dwordx4 v[2:3], off
	v_lshl_add_u64 v[2:3], v[116:117], 1, s[34:35]
	s_add_i32 m0, s4, 0x2000
	s_cmp_lg_u32 0, -1
	global_load_lds_dwordx4 v[2:3], off
	s_cselect_b32 s0, 0, 0
	v_lshlrev_b32_e32 v10, 1, v4
	v_lshlrev_b32_e32 v4, 3, v4
	s_add_i32 s1, s0, 0x8000
	v_and_b32_e32 v4, 0x70, v4
	v_lshl_add_u32 v124, v6, 7, s1
	s_movk_i32 s1, 0x60
	v_and_b32_e32 v3, 32, v10
	v_bitop3_b32 v128, v184, v4, s1 bitop3:0x36
	s_movk_i32 s1, 0x118
	v_and_b32_e32 v2, 0xc0, v8
	s_waitcnt vmcnt(0)
	v_lshl_add_u64 v[118:119], s[24:25], 0, v[0:1]
	v_and_or_b32 v0, v9, s1, v3
	v_mov_b32_e32 v15, v185
	v_bitop3_b32 v125, v7, v4, 16 bitop3:0x6c
	v_bitop3_b32 v126, v184, v4, 32 bitop3:0x36
	v_bitop3_b32 v127, v184, v4, 64 bitop3:0x36
	v_cmp_gt_u32_e64 s[6:7], 32, v5
	v_lshl_add_u32 v123, v6, 2, v122
	v_add3_u32 v129, v2, s0, v0
	v_mov_b32_e32 v0, v185
	v_mov_b32_e32 v1, v185
	v_mov_b32_e32 v2, v185
	v_mov_b32_e32 v3, v185
	v_mov_b32_e32 v4, v185
	v_mov_b32_e32 v5, v185
	v_mov_b32_e32 v6, v185
	v_mov_b32_e32 v7, v185
	v_mov_b32_e32 v8, v185
	v_mov_b32_e32 v9, v185
	v_mov_b32_e32 v10, v185
	v_mov_b32_e32 v11, v185
	v_mov_b32_e32 v12, v185
	v_mov_b32_e32 v13, v185
	v_mov_b64_e32 v[30:31], v[14:15]
	v_mov_b64_e32 v[46:47], v[14:15]
	v_mov_b64_e32 v[62:63], v[14:15]
	v_mov_b64_e32 v[28:29], v[12:13]
	v_mov_b64_e32 v[26:27], v[10:11]
	v_mov_b64_e32 v[24:25], v[8:9]
	v_mov_b64_e32 v[22:23], v[6:7]
	v_mov_b64_e32 v[20:21], v[4:5]
	v_mov_b64_e32 v[18:19], v[2:3]
	v_mov_b64_e32 v[16:17], v[0:1]
	v_mov_b64_e32 v[44:45], v[12:13]
	v_mov_b64_e32 v[42:43], v[10:11]
	v_mov_b64_e32 v[40:41], v[8:9]
	v_mov_b64_e32 v[38:39], v[6:7]
	v_mov_b64_e32 v[36:37], v[4:5]
	v_mov_b64_e32 v[34:35], v[2:3]
	v_mov_b64_e32 v[32:33], v[0:1]
	v_mov_b64_e32 v[60:61], v[12:13]
	v_mov_b64_e32 v[58:59], v[10:11]
	v_mov_b64_e32 v[56:57], v[8:9]
	v_mov_b64_e32 v[54:55], v[6:7]
	v_mov_b64_e32 v[52:53], v[4:5]
	v_mov_b64_e32 v[50:51], v[2:3]
	v_mov_b64_e32 v[48:49], v[0:1]
	v_mov_b32_e32 v160, 0x80000000
	v_mov_b32_e32 v161, 0x80000000
	v_mov_b32_e32 v162, 0x80000000
	v_mov_b32_e32 v163, 0x80000000
	v_mov_b32_e32 v164, 0x80000000
	v_mov_b32_e32 v165, 0x80000000
	v_mov_b32_e32 v166, 0x80000000
	v_mov_b32_e32 v167, 0x80000000
	v_mov_b32_e32 v168, 0x80000000
	v_mov_b32_e32 v169, 0x80000000
	v_mov_b32_e32 v170, 0x80000000
	v_mov_b32_e32 v171, 0x80000000
	v_mov_b32_e32 v172, 0x80000000
	v_mov_b32_e32 v173, 0x80000000
	v_mov_b32_e32 v174, 0x80000000
	v_mov_b32_e32 v175, 0x80000000
	v_readlane_b32 s54, v254, 48
	s_waitcnt vmcnt(0) lgkmcnt(0)
	s_barrier
	s_and_b32 s53, s5, 1
	s_cmp_eq_u32 s5, 31
	s_movk_i32 s0, 0x2000
	s_cbranch_scc1 .LBB0_152

.LBB0_169:
	s_and_b32 s0, s64, 31
	s_lshl_b32 s0, s0, 6
	s_or_b32 s14, s14, s0
	s_mul_i32 s0, s15, 0x600
	s_mul_hi_u32 s1, s14, 0x600
	s_add_i32 s1, s1, s0
	s_mul_i32 s0, s14, 0x600
	s_add_u32 s0, s38, s0
	s_addc_u32 s1, s39, s1
	s_mul_hi_i32 s3, s2, 0xc0000
	s_mul_i32 s2, s2, 0xc0000
	v_mov_b32_e32 v158, v218
	s_add_u32 s4, s28, s2
	v_mov_b32_e32 v4, v218
	s_addc_u32 s5, s29, s3
	s_add_i32 s3, 0, 0x14000
	v_and_b32_e32 v0, 0x3fffffc0, v4
	v_lshl_add_u32 v159, v0, 2, s3
	v_ashrrev_i32_e32 v0, 6, v4
	v_and_b32_e32 v6, 31, v4
	v_readfirstlane_b32 s3, v0
	v_lshlrev_b32_e32 v0, 5, v0
	v_and_or_b32 v0, v0, 32, v6
	v_mul_u32_u24_e32 v0, 0x300, v0
	v_ashrrev_i32_e32 v2, 7, v4
	v_lshlrev_b32_e32 v184, 1, v0
	v_mul_lo_u32 v2, v2, s60
	v_lshl_add_u64 v[0:1], s[0:1], 0, v[184:185]
	v_ashrrev_i32_e32 v3, 31, v2
	v_lshl_add_u64 v[0:1], v[2:3], 1, v[0:1]
	v_lshrrev_b32_e32 v2, 1, v4
	v_and_b32_e32 v5, 63, v4
	v_and_b32_e32 v184, 16, v2
	v_lshl_add_u64 v[0:1], v[0:1], 0, v[184:185]
	s_lshl_b32 s6, s3, 10
	v_lshlrev_b32_e32 v3, 4, v5
	global_load_dwordx4 v[96:99], v[0:1], off
	global_load_dwordx4 v[100:103], v[0:1], off offset:32
	global_load_dwordx4 v[104:107], v[0:1], off offset:64
	global_load_dwordx4 v[108:111], v[0:1], off offset:96
	global_load_dwordx4 v[112:115], v[0:1], off offset:128
	global_load_dwordx4 v[116:119], v[0:1], off offset:160
	global_load_dwordx4 v[120:123], v[0:1], off offset:192
	global_load_dwordx4 v[124:127], v[0:1], off offset:224
	global_load_dwordx4 v[128:131], v[0:1], off offset:256
	global_load_dwordx4 v[132:135], v[0:1], off offset:288
	global_load_dwordx4 v[136:139], v[0:1], off offset:320
	global_load_dwordx4 v[140:143], v[0:1], off offset:352
	v_or_b32_e32 v0, s6, v3
	s_mov_b32 s0, 0x2aaaaaab
	v_mul_hi_i32 v1, v0, s0
	v_lshrrev_b32_e32 v7, 31, v1
	v_ashrrev_i32_e32 v1, 6, v1
	v_add_u32_e32 v1, v1, v7
	v_mul_i32_i24_e32 v7, 0x180, v1
	v_sub_u32_e32 v7, v0, v7
	v_ashrrev_i32_e32 v7, 4, v7
	v_lshrrev_b32_e32 v8, 1, v1
	v_bitop3_b32 v7, v8, v7, 7 bitop3:0x6c
	v_mul_i32_i24_e32 v1, 0xc0, v1
	v_lshl_add_u32 v146, v7, 3, v1
	v_add_u32_e32 v1, 0x2000, v0
	v_mul_hi_i32 v7, v1, s0
	v_lshrrev_b32_e32 v8, 31, v7
	v_ashrrev_i32_e32 v7, 6, v7
	v_add_u32_e32 v7, v7, v8
	v_mul_i32_i24_e32 v8, 0x180, v7
	v_sub_u32_e32 v1, v1, v8
	v_ashrrev_i32_e32 v1, 4, v1
	v_lshrrev_b32_e32 v8, 1, v7
	v_bitop3_b32 v1, v8, v1, 7 bitop3:0x6c
	v_mul_i32_i24_e32 v7, 0xc0, v7
	v_add_u32_e32 v0, 0x4000, v0
	v_lshl_add_u32 v148, v1, 3, v7
	v_mul_hi_i32 v1, v0, s0
	v_lshrrev_b32_e32 v7, 31, v1
	v_ashrrev_i32_e32 v1, 6, v1
	v_add_u32_e32 v1, v1, v7
	v_mul_i32_i24_e32 v7, 0x180, v1
	v_sub_u32_e32 v0, v0, v7
	v_ashrrev_i32_e32 v0, 4, v0
	v_lshrrev_b32_e32 v7, 1, v1
	v_bitop3_b32 v0, v7, v0, 7 bitop3:0x6c
	v_mul_i32_i24_e32 v1, 0xc0, v1
	v_lshlrev_b32_e32 v7, 3, v5
	s_lshl_b32 s0, s3, 6
	v_lshl_add_u32 v150, v0, 3, v1
	v_and_b32_e32 v1, 32, v4
	s_and_b32 s0, s0, 64
	v_and_b32_e32 v8, 24, v7
	v_or3_b32 v1, v8, v1, s0
	s_ashr_i32 s0, s6, 8
	s_and_b32 s1, s0, 0xfffff0
	s_lshr_b32 s0, s0, 1
	v_bfe_u32 v0, v4, 2, 2
	s_and_b32 s0, s0, 4
	v_and_or_b32 v0, v2, 8, v0
	s_or_b32 s0, s1, s0
	v_or_b32_e32 v8, s0, v0
	s_add_i32 s0, s6, 0x2000
	s_ashr_i32 s0, s0, 8
	s_lshl_b32 s2, s64, 2
	s_and_b32 s1, s0, 0xfffff0
	s_lshr_b32 s0, s0, 1
	s_and_b32 s2, s2, 28
	s_and_b32 s0, s0, 4
	s_or_b32 s0, s1, s0
	s_mulk_i32 s2, 0x6000
	v_or_b32_e32 v0, s0, v0
	s_add_u32 s0, s4, s2
	s_addc_u32 s1, s5, 0
	s_add_i32 s30, s6, 0
	v_ashrrev_i32_e32 v147, 31, v146
	v_mad_i32_i24 v152, v8, s60, v1
	v_mad_i32_i24 v154, v0, s60, v1
	s_add_i32 m0, s30, 0x8000
	v_lshl_add_u64 v[0:1], v[146:147], 1, s[0:1]
	v_ashrrev_i32_e32 v149, 31, v148
	s_waitcnt lgkmcnt(0)
	s_barrier
	global_load_lds_dwordx4 v[0:1], off
	v_lshl_add_u64 v[0:1], v[148:149], 1, s[0:1]
	s_add_i32 m0, s30, 0xa000
	v_ashrrev_i32_e32 v151, 31, v150
	global_load_lds_dwordx4 v[0:1], off
	v_lshl_add_u64 v[0:1], v[150:151], 1, s[0:1]
	s_add_i32 m0, s30, 0xc000
	v_ashrrev_i32_e32 v153, 31, v152
	global_load_lds_dwordx4 v[0:1], off
	v_lshl_add_u64 v[0:1], v[152:153], 1, s[0:1]
	s_mov_b32 m0, s30
	v_ashrrev_i32_e32 v155, 31, v154
	global_load_lds_dwordx4 v[0:1], off
	v_lshl_add_u64 v[0:1], v[154:155], 1, s[0:1]
	s_add_i32 m0, s30, 0x2000
	s_cmp_lg_u32 0, -1
	global_load_lds_dwordx4 v[0:1], off
	s_cselect_b32 s0, 0, 0
	s_add_i32 s1, s0, 0x8000
	v_lshlrev_b32_e32 v8, 1, v4
	v_lshlrev_b32_e32 v1, 3, v4
	v_mov_b32_e32 v4, s1
	s_movk_i32 s1, 0x180
	v_and_b32_e32 v1, 0x70, v1
	v_mad_u32_u24 v161, v6, s1, v4
	s_movk_i32 s1, 0x60
	v_and_b32_e32 v0, 32, v8
	v_bitop3_b32 v165, v184, v1, s1 bitop3:0x36
	s_movk_i32 s1, 0x118
	v_and_b32_e32 v3, 0xc0, v3
	v_and_or_b32 v0, v7, s1, v0
	s_waitcnt vmcnt(0)
	v_add3_u32 v166, v3, s0, v0
	s_and_b32 s0, s64, 7
	v_mov_b32_e32 v14, v185
	v_mov_b32_e32 v15, v185
	v_bitop3_b32 v162, v2, v1, 16 bitop3:0x6c
	v_bitop3_b32 v163, v184, v1, 32 bitop3:0x36
	v_bitop3_b32 v164, v184, v1, 64 bitop3:0x36
	v_cmp_gt_u32_e64 s[6:7], 32, v5
	v_lshl_add_u32 v160, v6, 2, v159
	s_lshl_b32 s0, s0, 8
	v_mov_b32_e32 v0, v185
	v_mov_b32_e32 v1, v185
	v_mov_b32_e32 v2, v185
	v_mov_b32_e32 v3, v185
	v_mov_b32_e32 v4, v185
	v_mov_b32_e32 v5, v185
	v_mov_b32_e32 v6, v185
	v_mov_b32_e32 v7, v185
	v_mov_b32_e32 v8, v185
	v_mov_b32_e32 v9, v185
	v_mov_b32_e32 v10, v185
	v_mov_b32_e32 v11, v185
	v_mov_b32_e32 v12, v185
	v_mov_b32_e32 v13, v185
	v_mov_b64_e32 v[30:31], v[14:15]
	v_mov_b64_e32 v[46:47], v[14:15]
	v_mov_b64_e32 v[62:63], v[14:15]
	s_mov_b32 s31, 0
	s_or_b32 s34, s0, 64
	v_mov_b32_e32 v167, 0
	v_mov_b64_e32 v[28:29], v[12:13]
	v_mov_b64_e32 v[26:27], v[10:11]
	v_mov_b64_e32 v[24:25], v[8:9]
	v_mov_b64_e32 v[22:23], v[6:7]
	v_mov_b64_e32 v[20:21], v[4:5]
	v_mov_b64_e32 v[18:19], v[2:3]
	v_mov_b64_e32 v[16:17], v[0:1]
	v_mov_b64_e32 v[44:45], v[12:13]
	v_mov_b64_e32 v[42:43], v[10:11]
	v_mov_b64_e32 v[40:41], v[8:9]
	v_mov_b64_e32 v[38:39], v[6:7]
	v_mov_b64_e32 v[36:37], v[4:5]
	v_mov_b64_e32 v[34:35], v[2:3]
	v_mov_b64_e32 v[32:33], v[0:1]
	v_mov_b64_e32 v[60:61], v[12:13]
	v_mov_b64_e32 v[58:59], v[10:11]
	v_mov_b64_e32 v[56:57], v[8:9]
	v_mov_b64_e32 v[54:55], v[6:7]
	v_mov_b64_e32 v[52:53], v[4:5]
	v_mov_b64_e32 v[50:51], v[2:3]
	v_mov_b64_e32 v[48:49], v[0:1]
	v_mov_b32_e32 v168, 0
	s_waitcnt vmcnt(0) lgkmcnt(0)
	s_barrier
	s_and_b32 s35, s31, 1
	s_cmp_eq_u32 s31, 31
	s_cbranch_scc1 .LBB0_171

.LBB0_214:
	s_cmp_lt_i32 s61, 3
	s_cselect_b64 vcc, -1, 0
	s_and_b64 s[0:1], vcc, exec
	v_readlane_b32 s0, v254, 56
	v_mov_b32_e32 v128, 0x3dd53b94
	v_readlane_b32 s1, v254, 57
	v_cndmask_b32_e32 v146, 1.0, v128, vcc
	v_bfrev_b32_e32 v128, 60
	v_mov_b32_e32 v129, 0x3b800000
	s_cselect_b32 s75, s1, s27
	s_cselect_b32 s74, s0, s26
	s_lshl_b32 s0, s62, 8
	v_cndmask_b32_e32 v147, v128, v129, vcc
	v_mov_b32_e32 v128, v218
	s_add_i32 s0, s0, s82
	s_cmp_eq_u32 s61, 2
	v_and_or_b32 v184, v128, 15, s0
	v_lshl_add_u64 v[140:141], v[184:185], 3, s[74:75]
	v_bfe_u32 v148, v128, 4, 2
	global_load_dwordx2 v[202:203], v[140:141], off
	global_load_dwordx2 v[204:205], v[140:141], off offset:128
	global_load_dwordx2 v[206:207], v[140:141], off offset:256
	global_load_dwordx2 v[208:209], v[140:141], off offset:384
	global_load_dwordx2 v[210:211], v[140:141], off offset:1024
	global_load_dwordx2 v[212:213], v[140:141], off offset:1152
	global_load_dwordx2 v[214:215], v[140:141], off offset:1280
	global_load_dwordx2 v[216:217], v[140:141], off offset:1408
	v_lshlrev_b32_e32 v149, 3, v148
	s_cselect_b64 s[84:85], -1, 0
	s_cmp_lg_u32 s61, 2
	s_waitcnt vmcnt(0)
	v_mov_b64_e32 v[128:129], v[202:203]
	v_ffbh_u32_e32 v130, v129
	v_min_u32_e32 v130, 32, v130
	v_lshlrev_b64 v[128:129], v130, v[128:129]
	v_min_u32_e32 v128, 1, v128
	v_or_b32_e32 v128, v129, v128
	v_cvt_f32_u32_e32 v128, v128
	v_sub_u32_e32 v129, 32, v130
	v_ldexp_f32 v128, v128, v129
	v_mul_f32_e32 v128, 0x33800000, v128
	v_fmaak_f32 v128, v147, v128, 0x358637bd
	v_rsq_f32_e32 v128, v128
	s_nop 0
	v_mul_f32_e32 v150, v146, v128
	v_pk_mul_f32 v[130:131], v[114:115], v[150:151] op_sel_hi:[1,0]
	v_pk_mul_f32 v[128:129], v[112:113], v[150:151] op_sel_hi:[1,0]
	v_pk_mul_f32 v[114:115], v[118:119], v[150:151] op_sel_hi:[1,0]
	v_pk_mul_f32 v[112:113], v[116:117], v[150:151] op_sel_hi:[1,0]
	v_pk_mul_f32 v[122:123], v[122:123], v[150:151] op_sel_hi:[1,0]
	v_pk_mul_f32 v[142:143], v[120:121], v[150:151] op_sel_hi:[1,0]
	v_pk_mul_f32 v[118:119], v[126:127], v[150:151] op_sel_hi:[1,0]
	v_pk_mul_f32 v[120:121], v[124:125], v[150:151] op_sel_hi:[1,0]
	v_lshlrev_b32_e32 v125, 8, v184
	v_lshlrev_b32_e32 v116, 2, v149
	s_cbranch_scc1 .LBB0_216
	v_and_b32_e32 v126, 0x7cf00, v125
	v_mov_b32_e32 v127, v185
	v_lshl_add_u64 v[126:127], s[18:19], 0, v[126:127]
	v_mov_b32_e32 v117, v185
	v_lshl_add_u64 v[126:127], v[126:127], 0, v[116:117]
	global_load_dwordx4 v[150:153], v[126:127], off offset:128
	global_load_dwordx4 v[154:157], v[126:127], off offset:144
	global_load_dwordx4 v[158:161], v[126:127], off
	global_load_dwordx4 v[162:165], v[126:127], off offset:16
	s_waitcnt vmcnt(3)
	v_pk_mul_f32 v[126:127], v[122:123], v[152:153]
	v_pk_mul_f32 v[166:167], v[142:143], v[150:151]
	s_waitcnt vmcnt(2)
	v_pk_mul_f32 v[168:169], v[118:119], v[156:157]
	v_pk_mul_f32 v[170:171], v[120:121], v[154:155]
	v_pk_mul_f32 v[152:153], v[130:131], v[152:153]
	v_pk_mul_f32 v[150:151], v[128:129], v[150:151]
	v_pk_mul_f32 v[156:157], v[114:115], v[156:157]
	v_pk_mul_f32 v[154:155], v[112:113], v[154:155]
	s_waitcnt vmcnt(1)
	v_pk_fma_f32 v[130:131], v[130:131], v[160:161], v[126:127] neg_lo:[0,0,1] neg_hi:[0,0,1]
	v_pk_fma_f32 v[128:129], v[128:129], v[158:159], v[166:167] neg_lo:[0,0,1] neg_hi:[0,0,1]
	s_waitcnt vmcnt(0)
	v_pk_fma_f32 v[114:115], v[114:115], v[164:165], v[168:169] neg_lo:[0,0,1] neg_hi:[0,0,1]
	v_pk_fma_f32 v[112:113], v[112:113], v[162:163], v[170:171] neg_lo:[0,0,1] neg_hi:[0,0,1]
	v_pk_fma_f32 v[122:123], v[122:123], v[160:161], v[152:153]
	v_pk_fma_f32 v[142:143], v[142:143], v[158:159], v[150:151]
	v_pk_fma_f32 v[118:119], v[118:119], v[164:165], v[156:157]
	v_pk_fma_f32 v[120:121], v[120:121], v[162:163], v[154:155]
.LBB0_216:
	s_movk_i32 s0, 0x600
	v_lshlrev_b32_e32 v124, 4, v148
	v_mul_lo_u32 v127, v184, s0
	v_or_b32_e32 v117, v127, v124
	v_mul_lo_u32 v126, v184, s5
	v_cvt_pk_bf16_f32 v128, v128, v129
	v_cvt_pk_bf16_f32 v129, v130, v131
	v_cvt_pk_bf16_f32 v130, v112, v113
	v_cvt_pk_bf16_f32 v131, v114, v115
	global_store_dwordx4 v117, v[128:131], s[72:73]
	v_or_b32_e32 v117, v126, v124
	v_cvt_pk_bf16_f32 v112, v142, v143
	v_cvt_pk_bf16_f32 v113, v122, v123
	v_cvt_pk_bf16_f32 v114, v120, v121
	v_cvt_pk_bf16_f32 v115, v118, v119
	global_store_dwordx4 v117, v[112:115], s[70:71]
	s_nop 1
	v_mov_b64_e32 v[112:113], v[204:205]
	s_andn2_b64 vcc, exec, s[84:85]
	v_ffbh_u32_e32 v114, v113
	v_min_u32_e32 v114, 32, v114
	v_lshlrev_b64 v[112:113], v114, v[112:113]
	v_min_u32_e32 v112, 1, v112
	v_or_b32_e32 v112, v113, v112
	v_cvt_f32_u32_e32 v112, v112
	v_sub_u32_e32 v113, 32, v114
	v_ldexp_f32 v112, v112, v113
	v_mul_f32_e32 v112, 0x33800000, v112
	v_fmaak_f32 v112, v147, v112, 0x358637bd
	v_rsq_f32_e32 v112, v112
	v_cndmask_b32_e64 v113, 0, 1, s[84:85]
	v_cmp_ne_u32_e64 s[8:9], 1, v113
	v_mul_f32_e32 v118, v146, v112
	v_pk_mul_f32 v[114:115], v[98:99], v[118:119] op_sel_hi:[1,0]
	v_pk_mul_f32 v[112:113], v[96:97], v[118:119] op_sel_hi:[1,0]
	v_pk_mul_f32 v[98:99], v[102:103], v[118:119] op_sel_hi:[1,0]
	v_pk_mul_f32 v[96:97], v[100:101], v[118:119] op_sel_hi:[1,0]
	v_pk_mul_f32 v[106:107], v[106:107], v[118:119] op_sel_hi:[1,0]
	v_pk_mul_f32 v[104:105], v[104:105], v[118:119] op_sel_hi:[1,0]
	v_pk_mul_f32 v[100:101], v[110:111], v[118:119] op_sel_hi:[1,0]
	v_pk_mul_f32 v[102:103], v[108:109], v[118:119] op_sel_hi:[1,0]
	s_cbranch_vccnz .LBB0_218
	s_mov_b32 s0, 0x7df00
	v_mov_b32_e32 v108, 0x1000
	v_bitop3_b32 v108, v125, s0, v108 bitop3:0xc8
	v_mov_b32_e32 v109, v185
	v_lshl_add_u64 v[108:109], s[18:19], 0, v[108:109]
	v_mov_b32_e32 v117, v185
	v_lshl_add_u64 v[122:123], v[108:109], 0, v[116:117]
	global_load_dwordx4 v[108:111], v[122:123], off offset:128
	global_load_dwordx4 v[118:121], v[122:123], off offset:144
	global_load_dwordx4 v[128:131], v[122:123], off
	global_load_dwordx4 v[148:151], v[122:123], off offset:16
	s_waitcnt vmcnt(3)
	v_pk_mul_f32 v[122:123], v[106:107], v[110:111]
	v_pk_mul_f32 v[142:143], v[104:105], v[108:109]
	s_waitcnt vmcnt(2)
	v_pk_mul_f32 v[152:153], v[100:101], v[120:121]
	v_pk_mul_f32 v[154:155], v[102:103], v[118:119]
	v_pk_mul_f32 v[110:111], v[114:115], v[110:111]
	v_pk_mul_f32 v[108:109], v[112:113], v[108:109]
	v_pk_mul_f32 v[120:121], v[98:99], v[120:121]
	v_pk_mul_f32 v[118:119], v[96:97], v[118:119]
	s_waitcnt vmcnt(1)
	v_pk_fma_f32 v[114:115], v[114:115], v[130:131], v[122:123] neg_lo:[0,0,1] neg_hi:[0,0,1]
	v_pk_fma_f32 v[112:113], v[112:113], v[128:129], v[142:143] neg_lo:[0,0,1] neg_hi:[0,0,1]
	s_waitcnt vmcnt(0)
	v_pk_fma_f32 v[98:99], v[98:99], v[150:151], v[152:153] neg_lo:[0,0,1] neg_hi:[0,0,1]
	v_pk_fma_f32 v[96:97], v[96:97], v[148:149], v[154:155] neg_lo:[0,0,1] neg_hi:[0,0,1]
	v_pk_fma_f32 v[106:107], v[106:107], v[130:131], v[110:111]
	v_pk_fma_f32 v[104:105], v[104:105], v[128:129], v[108:109]
	v_pk_fma_f32 v[100:101], v[100:101], v[150:151], v[120:121]
	v_pk_fma_f32 v[102:103], v[102:103], v[148:149], v[118:119]
.LBB0_218:
	v_add_u32_e32 v108, 0x6000, v127
	v_or_b32_e32 v109, v108, v124
	s_lshl_b32 s0, s5, 4
	v_cvt_pk_bf16_f32 v110, v112, v113
	v_cvt_pk_bf16_f32 v111, v114, v115
	v_cvt_pk_bf16_f32 v112, v96, v97
	v_cvt_pk_bf16_f32 v113, v98, v99
	global_store_dwordx4 v109, v[110:113], s[72:73]
	v_add_u32_e32 v109, s0, v126
	v_cvt_pk_bf16_f32 v96, v104, v105
	v_cvt_pk_bf16_f32 v97, v106, v107
	v_cvt_pk_bf16_f32 v98, v102, v103
	v_cvt_pk_bf16_f32 v99, v100, v101
	s_nop 0
	v_or_b32_e32 v110, v109, v124
	global_store_dwordx4 v110, v[96:99], s[70:71]
	s_nop 1
	v_mov_b64_e32 v[96:97], v[206:207]
	s_and_b64 vcc, exec, s[8:9]
	v_ffbh_u32_e32 v98, v97
	v_min_u32_e32 v98, 32, v98
	v_lshlrev_b64 v[96:97], v98, v[96:97]
	v_min_u32_e32 v96, 1, v96
	v_or_b32_e32 v96, v97, v96
	v_cvt_f32_u32_e32 v96, v96
	v_sub_u32_e32 v97, 32, v98
	v_ldexp_f32 v96, v96, v97
	v_mul_f32_e32 v96, 0x33800000, v96
	v_fmaak_f32 v96, v147, v96, 0x358637bd
	v_rsq_f32_e32 v96, v96
	s_nop 0
	v_mul_f32_e32 v100, v146, v96
	v_pk_mul_f32 v[98:99], v[82:83], v[100:101] op_sel_hi:[1,0]
	v_pk_mul_f32 v[96:97], v[80:81], v[100:101] op_sel_hi:[1,0]
	v_pk_mul_f32 v[82:83], v[86:87], v[100:101] op_sel_hi:[1,0]
	v_pk_mul_f32 v[80:81], v[84:85], v[100:101] op_sel_hi:[1,0]
	v_pk_mul_f32 v[90:91], v[90:91], v[100:101] op_sel_hi:[1,0]
	v_pk_mul_f32 v[88:89], v[88:89], v[100:101] op_sel_hi:[1,0]
	v_pk_mul_f32 v[84:85], v[94:95], v[100:101] op_sel_hi:[1,0]
	v_pk_mul_f32 v[86:87], v[92:93], v[100:101] op_sel_hi:[1,0]
	s_cbranch_vccnz .LBB0_220
	s_mov_b32 s1, 0x7ef00
	v_mov_b32_e32 v92, 0x2000
	v_bitop3_b32 v92, v125, s1, v92 bitop3:0xc8
	v_mov_b32_e32 v93, v185
	v_lshl_add_u64 v[92:93], s[18:19], 0, v[92:93]
	v_mov_b32_e32 v117, v185
	v_lshl_add_u64 v[110:111], v[92:93], 0, v[116:117]
	global_load_dwordx4 v[92:95], v[110:111], off offset:128
	global_load_dwordx4 v[100:103], v[110:111], off offset:144
	global_load_dwordx4 v[104:107], v[110:111], off
	s_nop 0
	global_load_dwordx4 v[110:113], v[110:111], off offset:16
	s_waitcnt vmcnt(3)
	v_pk_mul_f32 v[114:115], v[90:91], v[94:95]
	v_pk_mul_f32 v[118:119], v[88:89], v[92:93]
	s_waitcnt vmcnt(2)
	v_pk_mul_f32 v[120:121], v[84:85], v[102:103]
	v_pk_mul_f32 v[122:123], v[86:87], v[100:101]
	v_pk_mul_f32 v[94:95], v[98:99], v[94:95]
	v_pk_mul_f32 v[92:93], v[96:97], v[92:93]
	v_pk_mul_f32 v[102:103], v[82:83], v[102:103]
	v_pk_mul_f32 v[100:101], v[80:81], v[100:101]
	s_waitcnt vmcnt(1)
	v_pk_fma_f32 v[98:99], v[98:99], v[106:107], v[114:115] neg_lo:[0,0,1] neg_hi:[0,0,1]
	v_pk_fma_f32 v[96:97], v[96:97], v[104:105], v[118:119] neg_lo:[0,0,1] neg_hi:[0,0,1]
	s_waitcnt vmcnt(0)
	v_pk_fma_f32 v[82:83], v[82:83], v[112:113], v[120:121] neg_lo:[0,0,1] neg_hi:[0,0,1]
	v_pk_fma_f32 v[80:81], v[80:81], v[110:111], v[122:123] neg_lo:[0,0,1] neg_hi:[0,0,1]
	v_pk_fma_f32 v[90:91], v[90:91], v[106:107], v[94:95]
	v_pk_fma_f32 v[88:89], v[88:89], v[104:105], v[92:93]
	v_pk_fma_f32 v[84:85], v[84:85], v[112:113], v[102:103]
	v_pk_fma_f32 v[86:87], v[86:87], v[110:111], v[100:101]
.LBB0_220:
	v_add_u32_e32 v92, 0x6000, v108
	v_or_b32_e32 v93, v92, v124
	v_cvt_pk_bf16_f32 v94, v96, v97
	v_cvt_pk_bf16_f32 v95, v98, v99
	v_cvt_pk_bf16_f32 v96, v80, v81
	v_cvt_pk_bf16_f32 v97, v82, v83
	global_store_dwordx4 v93, v[94:97], s[72:73]
	v_add_u32_e32 v93, s0, v109
	v_cvt_pk_bf16_f32 v80, v88, v89
	v_cvt_pk_bf16_f32 v81, v90, v91
	v_cvt_pk_bf16_f32 v82, v86, v87
	v_cvt_pk_bf16_f32 v83, v84, v85
	s_nop 0
	v_or_b32_e32 v94, v93, v124
	global_store_dwordx4 v94, v[80:83], s[70:71]
	s_nop 1
	v_mov_b64_e32 v[80:81], v[208:209]
	s_and_b64 vcc, exec, s[8:9]
	v_ffbh_u32_e32 v82, v81
	v_min_u32_e32 v82, 32, v82
	v_lshlrev_b64 v[80:81], v82, v[80:81]
	v_min_u32_e32 v80, 1, v80
	v_or_b32_e32 v80, v81, v80
	v_cvt_f32_u32_e32 v80, v80
	v_sub_u32_e32 v81, 32, v82
	v_ldexp_f32 v80, v80, v81
	v_mul_f32_e32 v80, 0x33800000, v80
	v_fmaak_f32 v80, v147, v80, 0x358637bd
	v_rsq_f32_e32 v80, v80
	s_nop 0
	v_mul_f32_e32 v84, v146, v80
	v_pk_mul_f32 v[82:83], v[66:67], v[84:85] op_sel_hi:[1,0]
	v_pk_mul_f32 v[80:81], v[64:65], v[84:85] op_sel_hi:[1,0]
	v_pk_mul_f32 v[66:67], v[70:71], v[84:85] op_sel_hi:[1,0]
	v_pk_mul_f32 v[64:65], v[68:69], v[84:85] op_sel_hi:[1,0]
	v_pk_mul_f32 v[74:75], v[74:75], v[84:85] op_sel_hi:[1,0]
	v_pk_mul_f32 v[72:73], v[72:73], v[84:85] op_sel_hi:[1,0]
	v_pk_mul_f32 v[68:69], v[78:79], v[84:85] op_sel_hi:[1,0]
	v_pk_mul_f32 v[70:71], v[76:77], v[84:85] op_sel_hi:[1,0]
	s_cbranch_vccnz .LBB0_222
	s_mov_b32 s1, 0x7ff00
	v_mov_b32_e32 v76, 0x3000
	v_bitop3_b32 v76, v125, s1, v76 bitop3:0xc8
	v_mov_b32_e32 v77, v185
	v_lshl_add_u64 v[76:77], s[18:19], 0, v[76:77]
	v_mov_b32_e32 v117, v185
	v_lshl_add_u64 v[94:95], v[76:77], 0, v[116:117]
	global_load_dwordx4 v[76:79], v[94:95], off offset:128
	global_load_dwordx4 v[84:87], v[94:95], off offset:144
	global_load_dwordx4 v[88:91], v[94:95], off
	s_nop 0
	global_load_dwordx4 v[94:97], v[94:95], off offset:16
	s_waitcnt vmcnt(3)
	v_pk_mul_f32 v[98:99], v[74:75], v[78:79]
	v_pk_mul_f32 v[100:101], v[72:73], v[76:77]
	s_waitcnt vmcnt(2)
	v_pk_mul_f32 v[102:103], v[68:69], v[86:87]
	v_pk_mul_f32 v[104:105], v[70:71], v[84:85]
	v_pk_mul_f32 v[78:79], v[82:83], v[78:79]
	v_pk_mul_f32 v[76:77], v[80:81], v[76:77]
	v_pk_mul_f32 v[86:87], v[66:67], v[86:87]
	v_pk_mul_f32 v[84:85], v[64:65], v[84:85]
	s_waitcnt vmcnt(1)
	v_pk_fma_f32 v[82:83], v[82:83], v[90:91], v[98:99] neg_lo:[0,0,1] neg_hi:[0,0,1]
	v_pk_fma_f32 v[80:81], v[80:81], v[88:89], v[100:101] neg_lo:[0,0,1] neg_hi:[0,0,1]
	s_waitcnt vmcnt(0)
	v_pk_fma_f32 v[66:67], v[66:67], v[96:97], v[102:103] neg_lo:[0,0,1] neg_hi:[0,0,1]
	v_pk_fma_f32 v[64:65], v[64:65], v[94:95], v[104:105] neg_lo:[0,0,1] neg_hi:[0,0,1]
	v_pk_fma_f32 v[74:75], v[74:75], v[90:91], v[78:79]
	v_pk_fma_f32 v[72:73], v[72:73], v[88:89], v[76:77]
	v_pk_fma_f32 v[68:69], v[68:69], v[96:97], v[86:87]
	v_pk_fma_f32 v[70:71], v[70:71], v[94:95], v[84:85]
.LBB0_222:
	v_add_u32_e32 v77, 0x6000, v92
	v_or_b32_e32 v76, v77, v124
	v_cvt_pk_bf16_f32 v78, v80, v81
	v_cvt_pk_bf16_f32 v79, v82, v83
	v_cvt_pk_bf16_f32 v80, v64, v65
	v_cvt_pk_bf16_f32 v81, v66, v67
	global_store_dwordx4 v76, v[78:81], s[72:73]
	v_add_u32_e32 v76, s0, v93
	v_cvt_pk_bf16_f32 v64, v72, v73
	v_cvt_pk_bf16_f32 v65, v74, v75
	v_cvt_pk_bf16_f32 v66, v70, v71
	v_cvt_pk_bf16_f32 v67, v68, v69
	s_nop 0
	v_or_b32_e32 v78, v76, v124
	v_add_u32_e32 v68, 0x80, v184
	v_mov_b32_e32 v69, v185
	global_store_dwordx4 v78, v[64:67], s[70:71]
	s_and_b64 vcc, exec, s[8:9]
	s_nop 0
	v_lshl_add_u64 v[64:65], v[68:69], 3, s[74:75]
	s_nop 1
	v_mov_b64_e32 v[64:65], v[210:211]
	v_ffbh_u32_e32 v66, v65
	v_min_u32_e32 v66, 32, v66
	v_lshlrev_b64 v[64:65], v66, v[64:65]
	v_min_u32_e32 v64, 1, v64
	v_or_b32_e32 v64, v65, v64
	v_cvt_f32_u32_e32 v64, v64
	v_sub_u32_e32 v65, 32, v66
	v_ldexp_f32 v64, v64, v65
	v_mul_f32_e32 v64, 0x33800000, v64
	v_fmaak_f32 v64, v147, v64, 0x358637bd
	v_rsq_f32_e32 v64, v64
	s_nop 0
	v_mul_f32_e32 v70, v146, v64
	v_pk_mul_f32 v[66:67], v[50:51], v[70:71] op_sel_hi:[1,0]
	v_pk_mul_f32 v[64:65], v[48:49], v[70:71] op_sel_hi:[1,0]
	v_pk_mul_f32 v[50:51], v[54:55], v[70:71] op_sel_hi:[1,0]
	v_pk_mul_f32 v[48:49], v[52:53], v[70:71] op_sel_hi:[1,0]
	v_pk_mul_f32 v[58:59], v[58:59], v[70:71] op_sel_hi:[1,0]
	v_pk_mul_f32 v[56:57], v[56:57], v[70:71] op_sel_hi:[1,0]
	v_pk_mul_f32 v[52:53], v[62:63], v[70:71] op_sel_hi:[1,0]
	v_pk_mul_f32 v[54:55], v[60:61], v[70:71] op_sel_hi:[1,0]
	s_cbranch_vccnz .LBB0_224
	v_lshlrev_b32_e32 v60, 8, v68
	v_and_b32_e32 v60, 0x7cf00, v60
	v_mov_b32_e32 v61, v185
	v_lshl_add_u64 v[60:61], s[18:19], 0, v[60:61]
	v_mov_b32_e32 v117, v185
	v_lshl_add_u64 v[78:79], v[60:61], 0, v[116:117]
	global_load_dwordx4 v[60:63], v[78:79], off offset:128
	global_load_dwordx4 v[68:71], v[78:79], off offset:144
	global_load_dwordx4 v[72:75], v[78:79], off
	s_nop 0
	global_load_dwordx4 v[78:81], v[78:79], off offset:16
	s_waitcnt vmcnt(3)
	v_pk_mul_f32 v[82:83], v[58:59], v[62:63]
	v_pk_mul_f32 v[84:85], v[56:57], v[60:61]
	s_waitcnt vmcnt(2)
	v_pk_mul_f32 v[86:87], v[52:53], v[70:71]
	v_pk_mul_f32 v[88:89], v[54:55], v[68:69]
	v_pk_mul_f32 v[62:63], v[66:67], v[62:63]
	v_pk_mul_f32 v[60:61], v[64:65], v[60:61]
	v_pk_mul_f32 v[70:71], v[50:51], v[70:71]
	v_pk_mul_f32 v[68:69], v[48:49], v[68:69]
	s_waitcnt vmcnt(1)
	v_pk_fma_f32 v[66:67], v[66:67], v[74:75], v[82:83] neg_lo:[0,0,1] neg_hi:[0,0,1]
	v_pk_fma_f32 v[64:65], v[64:65], v[72:73], v[84:85] neg_lo:[0,0,1] neg_hi:[0,0,1]
	s_waitcnt vmcnt(0)
	v_pk_fma_f32 v[50:51], v[50:51], v[80:81], v[86:87] neg_lo:[0,0,1] neg_hi:[0,0,1]
	v_pk_fma_f32 v[48:49], v[48:49], v[78:79], v[88:89] neg_lo:[0,0,1] neg_hi:[0,0,1]
	v_pk_fma_f32 v[58:59], v[58:59], v[74:75], v[62:63]
	v_pk_fma_f32 v[56:57], v[56:57], v[72:73], v[60:61]
	v_pk_fma_f32 v[52:53], v[52:53], v[80:81], v[70:71]
	v_pk_fma_f32 v[54:55], v[54:55], v[78:79], v[68:69]
.LBB0_224:
	v_add_u32_e32 v60, 0x1e000, v77
	v_or_b32_e32 v61, v60, v124
	s_mul_i32 s1, s5, 0x50
	v_cvt_pk_bf16_f32 v62, v64, v65
	v_cvt_pk_bf16_f32 v63, v66, v67
	v_cvt_pk_bf16_f32 v64, v48, v49
	v_cvt_pk_bf16_f32 v65, v50, v51
	global_store_dwordx4 v61, v[62:65], s[72:73]
	v_add_u32_e32 v61, s1, v76
	v_cvt_pk_bf16_f32 v48, v56, v57
	v_cvt_pk_bf16_f32 v49, v58, v59
	v_cvt_pk_bf16_f32 v50, v54, v55
	v_cvt_pk_bf16_f32 v51, v52, v53
	s_nop 0
	v_or_b32_e32 v62, v61, v124
	v_add_u32_e32 v52, 0x90, v184
	v_mov_b32_e32 v53, v185
	global_store_dwordx4 v62, v[48:51], s[70:71]
	s_and_b64 vcc, exec, s[8:9]
	s_nop 0
	v_lshl_add_u64 v[48:49], v[52:53], 3, s[74:75]
	s_nop 1
	v_mov_b64_e32 v[48:49], v[212:213]
	v_ffbh_u32_e32 v50, v49
	v_min_u32_e32 v50, 32, v50
	v_lshlrev_b64 v[48:49], v50, v[48:49]
	v_min_u32_e32 v48, 1, v48
	v_or_b32_e32 v48, v49, v48
	v_cvt_f32_u32_e32 v48, v48
	v_sub_u32_e32 v49, 32, v50
	v_ldexp_f32 v48, v48, v49
	v_mul_f32_e32 v48, 0x33800000, v48
	v_fmaak_f32 v48, v147, v48, 0x358637bd
	v_rsq_f32_e32 v48, v48
	s_nop 0
	v_mul_f32_e32 v54, v146, v48
	v_pk_mul_f32 v[50:51], v[34:35], v[54:55] op_sel_hi:[1,0]
	v_pk_mul_f32 v[48:49], v[32:33], v[54:55] op_sel_hi:[1,0]
	v_pk_mul_f32 v[34:35], v[38:39], v[54:55] op_sel_hi:[1,0]
	v_pk_mul_f32 v[32:33], v[36:37], v[54:55] op_sel_hi:[1,0]
	v_pk_mul_f32 v[42:43], v[42:43], v[54:55] op_sel_hi:[1,0]
	v_pk_mul_f32 v[40:41], v[40:41], v[54:55] op_sel_hi:[1,0]
	v_pk_mul_f32 v[36:37], v[46:47], v[54:55] op_sel_hi:[1,0]
	v_pk_mul_f32 v[38:39], v[44:45], v[54:55] op_sel_hi:[1,0]
	s_cbranch_vccnz .LBB0_226
	v_lshlrev_b32_e32 v44, 8, v52
	v_and_b32_e32 v44, 0x7df00, v44
	v_mov_b32_e32 v45, v185
	v_lshl_add_u64 v[44:45], s[18:19], 0, v[44:45]
	v_mov_b32_e32 v117, v185
	v_lshl_add_u64 v[62:63], v[44:45], 0, v[116:117]
	global_load_dwordx4 v[44:47], v[62:63], off offset:128
	global_load_dwordx4 v[52:55], v[62:63], off offset:144
	global_load_dwordx4 v[56:59], v[62:63], off
	s_nop 0
	global_load_dwordx4 v[62:65], v[62:63], off offset:16
	s_waitcnt vmcnt(3)
	v_pk_mul_f32 v[66:67], v[42:43], v[46:47]
	v_pk_mul_f32 v[68:69], v[40:41], v[44:45]
	s_waitcnt vmcnt(2)
	v_pk_mul_f32 v[70:71], v[36:37], v[54:55]
	v_pk_mul_f32 v[72:73], v[38:39], v[52:53]
	v_pk_mul_f32 v[46:47], v[50:51], v[46:47]
	v_pk_mul_f32 v[44:45], v[48:49], v[44:45]
	v_pk_mul_f32 v[54:55], v[34:35], v[54:55]
	v_pk_mul_f32 v[52:53], v[32:33], v[52:53]
	s_waitcnt vmcnt(1)
	v_pk_fma_f32 v[50:51], v[50:51], v[58:59], v[66:67] neg_lo:[0,0,1] neg_hi:[0,0,1]
	v_pk_fma_f32 v[48:49], v[48:49], v[56:57], v[68:69] neg_lo:[0,0,1] neg_hi:[0,0,1]
	s_waitcnt vmcnt(0)
	v_pk_fma_f32 v[34:35], v[34:35], v[64:65], v[70:71] neg_lo:[0,0,1] neg_hi:[0,0,1]
	v_pk_fma_f32 v[32:33], v[32:33], v[62:63], v[72:73] neg_lo:[0,0,1] neg_hi:[0,0,1]
	v_pk_fma_f32 v[42:43], v[42:43], v[58:59], v[46:47]
	v_pk_fma_f32 v[40:41], v[40:41], v[56:57], v[44:45]
	v_pk_fma_f32 v[36:37], v[36:37], v[64:65], v[54:55]
	v_pk_fma_f32 v[38:39], v[38:39], v[62:63], v[52:53]
.LBB0_226:
	v_add_u32_e32 v44, 0x6000, v60
	v_or_b32_e32 v45, v44, v124
	v_cvt_pk_bf16_f32 v46, v48, v49
	v_cvt_pk_bf16_f32 v47, v50, v51
	v_cvt_pk_bf16_f32 v48, v32, v33
	v_cvt_pk_bf16_f32 v49, v34, v35
	global_store_dwordx4 v45, v[46:49], s[72:73]
	v_add_u32_e32 v45, s0, v61
	v_cvt_pk_bf16_f32 v32, v40, v41
	v_cvt_pk_bf16_f32 v33, v42, v43
	v_cvt_pk_bf16_f32 v34, v38, v39
	v_cvt_pk_bf16_f32 v35, v36, v37
	s_nop 0
	v_or_b32_e32 v46, v45, v124
	v_add_u32_e32 v36, 0xa0, v184
	v_mov_b32_e32 v37, v185
	global_store_dwordx4 v46, v[32:35], s[70:71]
	s_and_b64 vcc, exec, s[8:9]
	s_nop 0
	v_lshl_add_u64 v[32:33], v[36:37], 3, s[74:75]
	s_nop 1
	v_mov_b64_e32 v[32:33], v[214:215]
	v_ffbh_u32_e32 v34, v33
	v_min_u32_e32 v34, 32, v34
	v_lshlrev_b64 v[32:33], v34, v[32:33]
	v_min_u32_e32 v32, 1, v32
	v_or_b32_e32 v32, v33, v32
	v_cvt_f32_u32_e32 v32, v32
	v_sub_u32_e32 v33, 32, v34
	v_ldexp_f32 v32, v32, v33
	v_mul_f32_e32 v32, 0x33800000, v32
	v_fmaak_f32 v32, v147, v32, 0x358637bd
	v_rsq_f32_e32 v32, v32
	s_nop 0
	v_mul_f32_e32 v38, v146, v32
	v_pk_mul_f32 v[34:35], v[18:19], v[38:39] op_sel_hi:[1,0]
	v_pk_mul_f32 v[32:33], v[16:17], v[38:39] op_sel_hi:[1,0]
	v_pk_mul_f32 v[18:19], v[22:23], v[38:39] op_sel_hi:[1,0]
	v_pk_mul_f32 v[16:17], v[20:21], v[38:39] op_sel_hi:[1,0]
	v_pk_mul_f32 v[26:27], v[26:27], v[38:39] op_sel_hi:[1,0]
	v_pk_mul_f32 v[24:25], v[24:25], v[38:39] op_sel_hi:[1,0]
	v_pk_mul_f32 v[20:21], v[30:31], v[38:39] op_sel_hi:[1,0]
	v_pk_mul_f32 v[22:23], v[28:29], v[38:39] op_sel_hi:[1,0]
	s_cbranch_vccnz .LBB0_228
	v_lshlrev_b32_e32 v28, 8, v36
	v_and_b32_e32 v28, 0x7ef00, v28
	v_mov_b32_e32 v29, v185
	v_lshl_add_u64 v[28:29], s[18:19], 0, v[28:29]
	v_mov_b32_e32 v117, v185
	v_lshl_add_u64 v[46:47], v[28:29], 0, v[116:117]
	global_load_dwordx4 v[28:31], v[46:47], off offset:128
	global_load_dwordx4 v[36:39], v[46:47], off offset:144
	global_load_dwordx4 v[40:43], v[46:47], off
	s_nop 0
	global_load_dwordx4 v[46:49], v[46:47], off offset:16
	s_waitcnt vmcnt(3)
	v_pk_mul_f32 v[50:51], v[26:27], v[30:31]
	v_pk_mul_f32 v[52:53], v[24:25], v[28:29]
	s_waitcnt vmcnt(2)
	v_pk_mul_f32 v[54:55], v[20:21], v[38:39]
	v_pk_mul_f32 v[56:57], v[22:23], v[36:37]
	v_pk_mul_f32 v[30:31], v[34:35], v[30:31]
	v_pk_mul_f32 v[28:29], v[32:33], v[28:29]
	v_pk_mul_f32 v[38:39], v[18:19], v[38:39]
	v_pk_mul_f32 v[36:37], v[16:17], v[36:37]
	s_waitcnt vmcnt(1)
	v_pk_fma_f32 v[34:35], v[34:35], v[42:43], v[50:51] neg_lo:[0,0,1] neg_hi:[0,0,1]
	v_pk_fma_f32 v[32:33], v[32:33], v[40:41], v[52:53] neg_lo:[0,0,1] neg_hi:[0,0,1]
	s_waitcnt vmcnt(0)
	v_pk_fma_f32 v[18:19], v[18:19], v[48:49], v[54:55] neg_lo:[0,0,1] neg_hi:[0,0,1]
	v_pk_fma_f32 v[16:17], v[16:17], v[46:47], v[56:57] neg_lo:[0,0,1] neg_hi:[0,0,1]
	v_pk_fma_f32 v[26:27], v[26:27], v[42:43], v[30:31]
	v_pk_fma_f32 v[24:25], v[24:25], v[40:41], v[28:29]
	v_pk_fma_f32 v[20:21], v[20:21], v[48:49], v[38:39]
	v_pk_fma_f32 v[22:23], v[22:23], v[46:47], v[36:37]
.LBB0_228:
	v_add_u32_e32 v28, 0x6000, v44
	v_or_b32_e32 v29, v28, v124
	v_cvt_pk_bf16_f32 v30, v32, v33
	v_cvt_pk_bf16_f32 v31, v34, v35
	v_cvt_pk_bf16_f32 v32, v16, v17
	v_cvt_pk_bf16_f32 v33, v18, v19
	global_store_dwordx4 v29, v[30:33], s[72:73]
	v_add_u32_e32 v29, s0, v45
	v_cvt_pk_bf16_f32 v16, v24, v25
	v_cvt_pk_bf16_f32 v17, v26, v27
	v_add_u32_e32 v184, 0xb0, v184
	v_or_b32_e32 v30, v29, v124
	v_cvt_pk_bf16_f32 v18, v22, v23
	v_cvt_pk_bf16_f32 v19, v20, v21
	global_store_dwordx4 v30, v[16:19], s[70:71]
	s_and_b64 vcc, exec, s[8:9]
	s_nop 0
	v_lshl_add_u64 v[16:17], v[184:185], 3, s[74:75]
	s_nop 1
	v_mov_b64_e32 v[16:17], v[216:217]
	v_ffbh_u32_e32 v18, v17
	v_min_u32_e32 v18, 32, v18
	v_lshlrev_b64 v[16:17], v18, v[16:17]
	v_min_u32_e32 v16, 1, v16
	v_or_b32_e32 v16, v17, v16
	v_cvt_f32_u32_e32 v16, v16
	v_sub_u32_e32 v17, 32, v18
	v_ldexp_f32 v16, v16, v17
	v_mul_f32_e32 v16, 0x33800000, v16
	v_fmaak_f32 v16, v147, v16, 0x358637bd
	v_rsq_f32_e32 v16, v16
	s_nop 0
	v_mul_f32_e32 v20, v146, v16
	v_pk_mul_f32 v[18:19], v[2:3], v[20:21] op_sel_hi:[1,0]
	v_pk_mul_f32 v[16:17], v[0:1], v[20:21] op_sel_hi:[1,0]
	v_pk_mul_f32 v[2:3], v[6:7], v[20:21] op_sel_hi:[1,0]
	v_pk_mul_f32 v[0:1], v[4:5], v[20:21] op_sel_hi:[1,0]
	v_pk_mul_f32 v[10:11], v[10:11], v[20:21] op_sel_hi:[1,0]
	v_pk_mul_f32 v[8:9], v[8:9], v[20:21] op_sel_hi:[1,0]
	v_pk_mul_f32 v[4:5], v[14:15], v[20:21] op_sel_hi:[1,0]
	v_pk_mul_f32 v[6:7], v[12:13], v[20:21] op_sel_hi:[1,0]
	s_cbranch_vccnz .LBB0_230
	v_lshlrev_b32_e32 v12, 8, v184
	v_and_b32_e32 v184, 0x7ff00, v12
	v_lshl_add_u64 v[12:13], s[18:19], 0, v[184:185]
	v_mov_b32_e32 v117, v185
	v_lshl_add_u64 v[30:31], v[12:13], 0, v[116:117]
	global_load_dwordx4 v[12:15], v[30:31], off offset:128
	global_load_dwordx4 v[20:23], v[30:31], off offset:144
	global_load_dwordx4 v[24:27], v[30:31], off
	s_nop 0
	global_load_dwordx4 v[30:33], v[30:31], off offset:16
	s_waitcnt vmcnt(3)
	v_pk_mul_f32 v[34:35], v[10:11], v[14:15]
	v_pk_mul_f32 v[36:37], v[8:9], v[12:13]
	s_waitcnt vmcnt(2)
	v_pk_mul_f32 v[38:39], v[4:5], v[22:23]
	v_pk_mul_f32 v[40:41], v[6:7], v[20:21]
	v_pk_mul_f32 v[14:15], v[18:19], v[14:15]
	v_pk_mul_f32 v[12:13], v[16:17], v[12:13]
	v_pk_mul_f32 v[22:23], v[2:3], v[22:23]
	v_pk_mul_f32 v[20:21], v[0:1], v[20:21]
	s_waitcnt vmcnt(1)
	v_pk_fma_f32 v[18:19], v[18:19], v[26:27], v[34:35] neg_lo:[0,0,1] neg_hi:[0,0,1]
	v_pk_fma_f32 v[16:17], v[16:17], v[24:25], v[36:37] neg_lo:[0,0,1] neg_hi:[0,0,1]
	s_waitcnt vmcnt(0)
	v_pk_fma_f32 v[2:3], v[2:3], v[32:33], v[38:39] neg_lo:[0,0,1] neg_hi:[0,0,1]
	v_pk_fma_f32 v[0:1], v[0:1], v[30:31], v[40:41] neg_lo:[0,0,1] neg_hi:[0,0,1]
	v_pk_fma_f32 v[10:11], v[10:11], v[26:27], v[14:15]
	v_pk_fma_f32 v[8:9], v[8:9], v[24:25], v[12:13]
	v_pk_fma_f32 v[4:5], v[4:5], v[32:33], v[22:23]
	v_pk_fma_f32 v[6:7], v[6:7], v[30:31], v[20:21]
